# dilated attention PV: V fragment LDS reads un-serialised with three rotating buffers, on top of the rewritten FFN-up epilogue
# speedup vs baseline: 1.0096x; 1.0019x over previous
; #define LAS __attribute__((address_space(3)))
; #define MFMA32(a, b, c) __builtin_amdgcn_mfma_f32_32x32x16_bf16((a), (b), (c), 0, 0, 0)
; template <int MODE> __device__ __forceinline__ void attn_unit(LAS unsigned char* lds, const AttnP& P, int b, int h, int qb) {
;     ...
;     auto pv = [&](const int voff) __attribute__((always_inline)) {
;         const LAS unsigned char* vb_ = lds + L_V + voff + r32 * VROWB + hi * 16;
; #pragma unroll
;         for (int j = 0; j < 4; ++j) { const bf16x8 v0 = *(const LAS bf16x8*)(vb_ + j * 32), v1 = *(const LAS bf16x8*)(vb_ + 32 * VROWB + j * 32);
;             oa0 = MFMA32(v0, pa[j], oa0); oa1 = MFMA32(v1, pa[j], oa1);
;             if (MODE == 1) { ob0 = MFMA32(v0, pb[j], ob0); ob1 = MFMA32(v1, pb[j], ob1); } }
;     };
.LBB0_768:
	s_mul_i32 s0, s16, 0x4400
	v_add_u32_e32 v10, s0, v221
	ds_read_b128 v[2:5], v10 offset:36864
	ds_read_b128 v[232:235], v10 offset:45568
	ds_read_b128 v[236:239], v10 offset:36896
	v_cvt_pk_bf16_f32 v6, v173, v177
	v_cvt_pk_bf16_f32 v7, v181, v185
	v_cvt_pk_bf16_f32 v8, v189, v205
	v_cvt_pk_bf16_f32 v9, v209, v207
	v_add_f32_e32 v222, v227, v170
	s_mov_b64 s[0:1], 0
	s_waitcnt lgkmcnt(2)
	v_mfma_f32_32x32x16_bf16 v[98:113], v[2:5], v[6:9], v[98:113]
	ds_read_b128 v[2:5], v10 offset:45600
	s_waitcnt lgkmcnt(2)
	v_mfma_f32_32x32x16_bf16 v[114:129], v[232:235], v[6:9], v[114:129]
	ds_read_b128 v[232:235], v10 offset:36928
	v_cvt_pk_bf16_f32 v6, v211, v191
	v_cvt_pk_bf16_f32 v7, v193, v183
	v_cvt_pk_bf16_f32 v8, v187, v175
	v_cvt_pk_bf16_f32 v9, v179, v169
	s_nop 0
	s_waitcnt lgkmcnt(2)
	v_mfma_f32_32x32x16_bf16 v[98:113], v[236:239], v[6:9], v[98:113]
	ds_read_b128 v[236:239], v10 offset:45632
	s_waitcnt lgkmcnt(2)
	v_mfma_f32_32x32x16_bf16 v[114:129], v[2:5], v[6:9], v[114:129]
	ds_read_b128 v[2:5], v10 offset:36960
	v_cvt_pk_bf16_f32 v6, v172, v176
	v_cvt_pk_bf16_f32 v7, v180, v184
	v_cvt_pk_bf16_f32 v8, v188, v204
	v_cvt_pk_bf16_f32 v9, v208, v206
	s_nop 0
	s_waitcnt lgkmcnt(2)
	v_mfma_f32_32x32x16_bf16 v[98:113], v[232:235], v[6:9], v[98:113]
	ds_read_b128 v[232:235], v10 offset:45664
	s_waitcnt lgkmcnt(2)
	v_mfma_f32_32x32x16_bf16 v[114:129], v[236:239], v[6:9], v[114:129]
	v_cvt_pk_bf16_f32 v6, v210, v190
	v_cvt_pk_bf16_f32 v7, v192, v182
	v_cvt_pk_bf16_f32 v8, v186, v174
	v_cvt_pk_bf16_f32 v9, v178, v168
	s_nop 0
	s_waitcnt lgkmcnt(1)
	v_mfma_f32_32x32x16_bf16 v[98:113], v[2:5], v[6:9], v[98:113]
	s_waitcnt lgkmcnt(0)
	v_mfma_f32_32x32x16_bf16 v[114:129], v[232:235], v[6:9], v[114:129]
	s_nop 8
	v_mov_b64_e32 v[18:19], v[98:99]
	v_mov_b64_e32 v[20:21], v[100:101]
	v_mov_b64_e32 v[22:23], v[102:103]
	v_mov_b64_e32 v[24:25], v[104:105]
	v_mov_b64_e32 v[26:27], v[106:107]
	v_mov_b64_e32 v[28:29], v[108:109]
	v_mov_b64_e32 v[30:31], v[110:111]
	v_mov_b64_e32 v[2:3], v[114:115]
	v_mov_b64_e32 v[32:33], v[112:113]
	v_mov_b64_e32 v[4:5], v[116:117]
	v_mov_b64_e32 v[6:7], v[118:119]
	v_mov_b64_e32 v[8:9], v[120:121]
	v_mov_b64_e32 v[10:11], v[122:123]
	v_mov_b64_e32 v[12:13], v[124:125]
	v_mov_b64_e32 v[14:15], v[126:127]
	v_mov_b64_e32 v[16:17], v[128:129]

; #define LAS __attribute__((address_space(3)))
; #define MFMA32(a, b, c) __builtin_amdgcn_mfma_f32_32x32x16_bf16((a), (b), (c), 0, 0, 0)
; template <int MODE> __device__ __forceinline__ void attn_unit(LAS unsigned char* lds, const AttnP& P, int b, int h, int qb) {
;     ...
;     auto pv = [&](const int voff) __attribute__((always_inline)) {
;         const LAS unsigned char* vb_ = lds + L_V + voff + r32 * VROWB + hi * 16;
; #pragma unroll
;         for (int j = 0; j < 4; ++j) { const bf16x8 v0 = *(const LAS bf16x8*)(vb_ + j * 32), v1 = *(const LAS bf16x8*)(vb_ + 32 * VROWB + j * 32);
;             oa0 = MFMA32(v0, pa[j], oa0); oa1 = MFMA32(v1, pa[j], oa1);
;             if (MODE == 1) { ob0 = MFMA32(v0, pb[j], ob0); ob1 = MFMA32(v1, pb[j], ob1); } }
;     };
.LBB0_791:
	s_lshl_b32 s0, s16, 10
	s_sub_i32 s0, s2, s0
	v_add3_u32 v10, s0, v220, v0
	ds_read_b128 v[2:5], v10 offset:36992
	ds_read_b128 v[232:235], v10 offset:45696
	ds_read_b128 v[236:239], v10 offset:37024
	v_cvt_pk_bf16_f32 v6, v173, v177
	v_cvt_pk_bf16_f32 v7, v181, v185
	v_cvt_pk_bf16_f32 v8, v189, v205
	v_cvt_pk_bf16_f32 v9, v209, v207
	v_add_f32_e32 v222, v227, v170
	s_mov_b64 s[0:1], 0
	s_waitcnt lgkmcnt(2)
	v_mfma_f32_32x32x16_bf16 v[98:113], v[2:5], v[6:9], v[98:113]
	ds_read_b128 v[2:5], v10 offset:45728
	s_waitcnt lgkmcnt(2)
	v_mfma_f32_32x32x16_bf16 v[114:129], v[232:235], v[6:9], v[114:129]
	ds_read_b128 v[232:235], v10 offset:37056
	v_cvt_pk_bf16_f32 v6, v211, v191
	v_cvt_pk_bf16_f32 v7, v193, v183
	v_cvt_pk_bf16_f32 v8, v187, v175
	v_cvt_pk_bf16_f32 v9, v179, v169
	s_nop 0
	s_waitcnt lgkmcnt(2)
	v_mfma_f32_32x32x16_bf16 v[98:113], v[236:239], v[6:9], v[98:113]
	ds_read_b128 v[236:239], v10 offset:45760
	s_waitcnt lgkmcnt(2)
	v_mfma_f32_32x32x16_bf16 v[114:129], v[2:5], v[6:9], v[114:129]
	ds_read_b128 v[2:5], v10 offset:37088
	v_cvt_pk_bf16_f32 v6, v172, v176
	v_cvt_pk_bf16_f32 v7, v180, v184
	v_cvt_pk_bf16_f32 v8, v188, v204
	v_cvt_pk_bf16_f32 v9, v208, v206
	s_nop 0
	s_waitcnt lgkmcnt(2)
	v_mfma_f32_32x32x16_bf16 v[98:113], v[232:235], v[6:9], v[98:113]
	ds_read_b128 v[232:235], v10 offset:45792
	s_waitcnt lgkmcnt(2)
	v_mfma_f32_32x32x16_bf16 v[114:129], v[236:239], v[6:9], v[114:129]
	v_cvt_pk_bf16_f32 v6, v210, v190
	v_cvt_pk_bf16_f32 v7, v192, v182
	v_cvt_pk_bf16_f32 v8, v186, v174
	v_cvt_pk_bf16_f32 v9, v178, v168
	s_nop 0
	s_waitcnt lgkmcnt(1)
	v_mfma_f32_32x32x16_bf16 v[98:113], v[2:5], v[6:9], v[98:113]
	s_waitcnt lgkmcnt(0)
	v_mfma_f32_32x32x16_bf16 v[114:129], v[232:235], v[6:9], v[114:129]
	s_nop 8
	v_mov_b64_e32 v[18:19], v[98:99]
	v_mov_b64_e32 v[20:21], v[100:101]
	v_mov_b64_e32 v[22:23], v[102:103]
	v_mov_b64_e32 v[24:25], v[104:105]
	v_mov_b64_e32 v[26:27], v[106:107]
	v_mov_b64_e32 v[28:29], v[108:109]
	v_mov_b64_e32 v[30:31], v[110:111]
	v_mov_b64_e32 v[2:3], v[114:115]
	v_mov_b64_e32 v[32:33], v[112:113]
	v_mov_b64_e32 v[4:5], v[116:117]
	v_mov_b64_e32 v[6:7], v[118:119]
	v_mov_b64_e32 v[8:9], v[120:121]
	v_mov_b64_e32 v[10:11], v[122:123]
	v_mov_b64_e32 v[12:13], v[124:125]
	v_mov_b64_e32 v[14:15], v[126:127]
	v_mov_b64_e32 v[16:17], v[128:129]
	s_andn2_b64 vcc, exec, s[48:49]
	s_cbranch_vccnz .LBB0_744
